# v4: + mixer C made block-cooperative (K/V tiles staged once per workgroup through LDS instead of 8x redundant per-wave global loads)
# speedup vs baseline: 1.1004x; 1.0143x over previous
.LBB0_393:
	s_or_b64 exec, exec, s[6:7]
	v_mov_b32_e32 v115, v200
	s_cmpk_gt_i32 s69, 0x7f
	s_mov_b64 s[6:7], -1
	s_cbranch_scc0 .LBB0_413
	s_cmpk_gt_u32 s69, 0xdf
	s_cbranch_scc0 .LBB0_403
	s_add_i32 s6, s69, 0xffffff20
	s_lshr_b32 s18, s6, 5
	v_readlane_b32 s6, v255, 7
	s_add_i32 s18, s18, s6
	s_not_b32 s6, s69
	s_lshl_b32 s6, s6, 7
	s_and_b32 s6, s6, 0xf80
	v_readlane_b32 s7, v255, 8
	v_and_b32_e32 v5, 15, v115
	s_add_i32 s10, s6, s7
	v_ashrrev_i32_e32 v4, 4, v115
	v_or_b32_e32 v72, s10, v5
	s_lshl_b32 s8, s18, 19
	v_readlane_b32 s6, v255, 9
	s_add_u32 s6, s6, s8
	v_readlane_b32 s7, v255, 10
	v_ashrrev_i32_e32 v73, 31, v72
	v_lshlrev_b32_e32 v74, 3, v4
	s_addc_u32 s7, s7, 0
	v_lshlrev_b64 v[0:1], 7, v[72:73]
	v_ashrrev_i32_e32 v75, 31, v74
	v_lshl_add_u64 v[0:1], s[6:7], 0, v[0:1]
	v_lshlrev_b64 v[2:3], 1, v[74:75]
	v_lshl_add_u64 v[0:1], v[0:1], 0, v[2:3]
	flat_load_dwordx4 v[16:19], v[0:1]
	flat_load_dwordx4 v[20:23], v[0:1] offset:64
	v_readlane_b32 s6, v255, 11
	s_add_u32 s6, s6, s8
	v_readlane_b32 s7, v255, 12
	s_addc_u32 s7, s7, 0
	v_readlane_b32 s9, v255, 13
	s_add_u32 s8, s9, s8
	v_readlane_b32 s9, v255, 14
	v_lshlrev_b32_e32 v136, 7, v5
	s_addc_u32 s9, s9, 0
	v_lshl_add_u64 v[76:77], s[6:7], 0, v[136:137]
	v_lshlrev_b32_e32 v136, 13, v5
	v_lshl_add_u64 v[0:1], s[8:9], 0, v[136:137]
	v_lshl_add_u64 v[78:79], v[0:1], 0, v[2:3]
	v_lshlrev_b32_e32 v0, 2, v115
	v_xor_b32_e32 v88, 64, v0
	v_xor_b32_e32 v89, 0x80, v0
	v_xor_b32_e32 v90, 0xc0, v0
	v_xor_b32_e32 v0, 1, v4
	v_cmp_gt_i32_e64 s[6:7], v0, v4
	v_xor_b32_e32 v0, 2, v4
	v_cmp_gt_i32_e64 s[8:9], v0, v4
	v_xor_b32_e32 v0, 3, v4
	v_mov_b32_e32 v136, v137
	s_ashr_i32 s12, s10, 6
	s_and_b32 s19, s10, 0xffffffc0
	v_lshlrev_b32_e32 v116, 2, v4
	v_cmp_gt_i32_e64 s[10:11], v0, v4
	v_lshl_add_u64 v[80:81], v[76:77], 0, v[2:3]
	v_mov_b32_e32 v138, v137
	v_mov_b32_e32 v139, v137
	v_mov_b64_e32 v[0:1], v[136:137]
	v_mov_b64_e32 v[4:5], v[136:137]
	v_mov_b64_e32 v[8:9], v[136:137]
	v_mov_b64_e32 v[12:13], v[136:137]
	s_add_i32 s20, s12, -2
	v_mov_b32_e32 v83, 0
	s_mov_b32 s14, s19
	v_mov_b64_e32 v[2:3], v[138:139]
	v_mov_b64_e32 v[6:7], v[138:139]
	v_mov_b64_e32 v[10:11], v[138:139]
	v_mov_b64_e32 v[14:15], v[138:139]
	s_mov_b32 s21, s12
	s_or_b32 s13, s12, 1
	s_mov_b32 s14, 0
	s_mov_b32 s15, 0
	s_mov_b32 s21, 0
	v_readlane_b32 s20, v255, 8
	v_lshrrev_b32_e32 v129, 3, v115
	s_lshr_b32 s20, s20, 1
	v_add_u32_e32 v129, s20, v129
	v_and_b32_e32 v134, 7, v115
	v_mul_u32_u24_e32 v128, 0xa0, v129
	v_lshl_add_u32 v128, v134, 4, v128
	v_and_b32_e32 v135, 15, v115
	v_mul_u32_u24_e32 v127, 0xa0, v135
	v_lshrrev_b32_e32 v135, 4, v115
	v_lshl_add_u32 v127, v135, 4, v127
	s_lshl_b32 s20, s20, 1
	v_mov_b32_e32 v156, s20
	v_lshrrev_b32_e32 v156, 2, v156
	s_lshl_b32 s20, s18, 19
	v_readlane_b32 s16, v255, 11
	v_readlane_b32 s17, v255, 12
	s_lshl_b32 s92, s13, 6
	s_add_u32 s16, s16, s20
	s_addc_u32 s17, s17, 0
	v_add_u32_e32 v135, s92, v129
	v_lshlrev_b32_e32 v135, 7, v135
	v_lshl_add_u32 v142, v134, 4, v135
	v_mov_b32_e32 v143, 0
	v_lshl_add_u64 v[130:131], s[16:17], 0, v[142:143]
	v_readlane_b32 s16, v255, 13
	v_readlane_b32 s17, v255, 14
	s_add_u32 s16, s16, s20
	s_addc_u32 s17, s17, 0
	v_lshlrev_b32_e32 v135, 13, v129
	v_lshl_add_u32 v135, v134, 4, v135
	s_lshl_b32 s92, s92, 1
	v_add_u32_e32 v142, s92, v135
	v_lshl_add_u64 v[132:133], s[16:17], 0, v[142:143]
	global_load_dwordx4 v[140:143], v[130:131], off
	global_load_dwordx4 v[144:147], v[132:133], off
	s_waitcnt vmcnt(0)
	ds_write_b128 v128, v[140:143] offset:16384
	ds_write_b128 v128, v[144:147] offset:26624
	s_waitcnt lgkmcnt(0)
	s_barrier
.Lcc_step:
	s_cmp_eq_u32 s13, 0
	s_cbranch_scc1 .Lcc_noload
	v_subrev_co_u32_e32 v130, vcc, 0x2000, v130
	s_nop 1
	v_subbrev_co_u32_e32 v131, vcc, 0, v131, vcc
	v_subrev_co_u32_e32 v132, vcc, 0x80, v132
	s_nop 1
	v_subbrev_co_u32_e32 v133, vcc, 0, v133, vcc
	global_load_dwordx4 v[140:143], v[130:131], off
	global_load_dwordx4 v[144:147], v[132:133], off
.Lcc_noload:
	s_cmp_gt_i32 s13, s12
	s_cbranch_scc1 .Lcc_after
	s_cmp_lg_u32 s15, 0
	s_cbranch_scc1 .Lcc_after
	v_add_u32_e32 v135, s14, v127
	ds_read_b128 v[100:103], v135 offset:16384
	ds_read_b128 v[68:71], v135 offset:16448
	ds_read_b128 v[96:99], v135 offset:18944
	ds_read_b128 v[64:67], v135 offset:19008
	ds_read_b128 v[92:95], v135 offset:21504
	ds_read_b128 v[60:63], v135 offset:21568
	ds_read_b128 v[84:87], v135 offset:24064
	ds_read_b128 v[56:59], v135 offset:24128
	ds_read_b128 v[52:55], v135 offset:26624
	ds_read_b128 v[48:51], v135 offset:26688
	ds_read_b128 v[44:47], v135 offset:29184
	ds_read_b128 v[40:43], v135 offset:29248
	ds_read_b128 v[36:39], v135 offset:31744
	ds_read_b128 v[32:35], v135 offset:31808
	ds_read_b128 v[28:31], v135 offset:34304
	ds_read_b128 v[24:27], v135 offset:34368
	s_lshl_b32 s19, s13, 6
	v_add_u32_e32 v91, s19, v116
	v_cmp_lt_i32_e32 vcc, v91, v72
	s_cmp_lg_u32 s13, 0
	s_waitcnt lgkmcnt(0)
	v_mfma_f32_16x16x32_bf16 v[84:87], v[84:87], v[16:19], 0
	v_mfma_f32_16x16x32_bf16 v[100:103], v[100:103], v[16:19], 0
	v_mfma_f32_16x16x32_bf16 v[68:71], v[68:71], v[20:23], v[100:103]
	v_mfma_f32_16x16x32_bf16 v[56:59], v[56:59], v[20:23], v[84:87]
	v_mfma_f32_16x16x32_bf16 v[92:95], v[92:95], v[16:19], 0
	s_nop 5
	v_mul_f32_e32 v82, 0x3e000000, v68
	v_mul_f32_e64 v84, |v82|, s80
	v_exp_f32_e32 v84, v84
	v_max_f32_e32 v82, 0, v82
	v_mfma_f32_16x16x32_bf16 v[60:63], v[60:63], v[20:23], v[92:95]
	v_add_f32_e32 v84, 1.0, v84
	v_log_f32_e32 v84, v84
	v_mfma_f32_16x16x32_bf16 v[96:99], v[96:99], v[16:19], 0
	v_fmac_f32_e32 v82, 0x3f317218, v84
	v_fma_f32 v68, v68, s70, -v82
	v_cndmask_b32_e32 v92, v241, v68, vcc
	v_sub_f32_e32 v68, 0, v82
	v_add_u32_e32 v82, 1, v91
	v_cndmask_b32_e32 v68, 0, v68, vcc
	v_cmp_lt_i32_e32 vcc, v82, v72
	v_mul_f32_e32 v82, 0x3e000000, v69
	v_mul_f32_e64 v84, |v82|, s80
	v_exp_f32_e32 v84, v84
	v_max_f32_e32 v82, 0, v82
	v_mfma_f32_16x16x32_bf16 v[64:67], v[64:67], v[20:23], v[96:99]
	v_add_f32_e32 v84, 1.0, v84
	v_log_f32_e32 v84, v84
	s_nop 0
	v_fmac_f32_e32 v82, 0x3f317218, v84
	v_fma_f32 v69, v69, s70, -v82
	v_cndmask_b32_e32 v98, v241, v69, vcc
	v_add_u32_e32 v69, 2, v91
	v_cndmask_b32_e64 v97, 0, -v82, vcc
	v_cmp_lt_i32_e32 vcc, v69, v72
	v_mul_f32_e32 v69, 0x3e000000, v70
	v_mul_f32_e64 v82, |v69|, s80
	v_exp_f32_e32 v82, v82
	v_max_f32_e32 v69, 0, v69
	v_add_f32_e32 v68, v97, v68
	v_add_f32_e32 v82, 1.0, v82
	v_log_f32_e32 v82, v82
	s_nop 0
	v_fmac_f32_e32 v69, 0x3f317218, v82
	v_cndmask_b32_e64 v99, 0, -v69, vcc
	v_fma_f32 v69, v70, s70, -v69
	v_cndmask_b32_e32 v100, v241, v69, vcc
	v_add_u32_e32 v69, 3, v91
	v_cmp_lt_i32_e32 vcc, v69, v72
	v_mul_f32_e32 v69, 0x3e000000, v71
	v_mul_f32_e64 v70, |v69|, s80
	v_exp_f32_e32 v70, v70
	v_max_f32_e32 v69, 0, v69
	v_add_f32_e32 v68, v99, v68
	v_add_f32_e32 v70, 1.0, v70
	v_log_f32_e32 v70, v70
	s_nop 0
	v_fmac_f32_e32 v69, 0x3f317218, v70
	v_cndmask_b32_e64 v101, 0, -v69, vcc
	v_fma_f32 v69, v71, s70, -v69
	v_cndmask_b32_e32 v102, v241, v69, vcc
	v_add_u32_e32 v69, 16, v91
	v_cmp_lt_i32_e32 vcc, v69, v72
	v_mul_f32_e32 v69, 0x3e000000, v64
	v_mul_f32_e64 v71, |v69|, s80
	v_exp_f32_e32 v71, v71
	v_max_f32_e32 v69, 0, v69
	v_add_f32_e32 v93, v101, v68
	ds_bpermute_b32 v94, v88, v93
	v_add_f32_e32 v71, 1.0, v71
	v_log_f32_e32 v71, v71
	ds_bpermute_b32 v95, v89, v93
	ds_bpermute_b32 v96, v90, v93
	s_waitcnt lgkmcnt(2)
	v_cndmask_b32_e64 v70, 0, v94, s[6:7]
	v_fmac_f32_e32 v69, 0x3f317218, v71
	v_fma_f32 v64, v64, s70, -v69
	v_cndmask_b32_e32 v103, v241, v64, vcc
	v_sub_f32_e32 v64, 0, v69
	v_add_u32_e32 v69, 17, v91
	v_cndmask_b32_e32 v64, 0, v64, vcc
	v_cmp_lt_i32_e32 vcc, v69, v72
	v_mul_f32_e32 v69, 0x3e000000, v65
	v_mul_f32_e64 v71, |v69|, s80
	v_exp_f32_e32 v71, v71
	v_max_f32_e32 v69, 0, v69
	s_waitcnt lgkmcnt(1)
	v_cndmask_b32_e64 v84, 0, v95, s[8:9]
	s_waitcnt lgkmcnt(0)
	v_cndmask_b32_e64 v68, 0, v96, s[10:11]
	v_add_f32_e32 v71, 1.0, v71
	v_log_f32_e32 v71, v71
	s_nop 0
	v_fmac_f32_e32 v69, 0x3f317218, v71
	v_fma_f32 v65, v65, s70, -v69
	v_cndmask_b32_e32 v105, v241, v65, vcc
	v_add_u32_e32 v65, 18, v91
	v_cndmask_b32_e64 v104, 0, -v69, vcc
	v_cmp_lt_i32_e32 vcc, v65, v72
	v_mul_f32_e32 v65, 0x3e000000, v66
	v_mul_f32_e64 v69, |v65|, s80
	v_exp_f32_e32 v69, v69
	v_max_f32_e32 v65, 0, v65
	v_add_f32_e32 v64, v104, v64
	v_add_f32_e32 v69, 1.0, v69
	v_log_f32_e32 v69, v69
	s_nop 0
	v_fmac_f32_e32 v65, 0x3f317218, v69
	v_cndmask_b32_e64 v106, 0, -v65, vcc
	v_fma_f32 v65, v66, s70, -v65
	v_cndmask_b32_e32 v107, v241, v65, vcc
	v_add_u32_e32 v65, 19, v91
	v_cmp_lt_i32_e32 vcc, v65, v72
	v_mul_f32_e32 v65, 0x3e000000, v67
	v_mul_f32_e64 v66, |v65|, s80
	v_exp_f32_e32 v66, v66
	v_max_f32_e32 v65, 0, v65
	v_add_f32_e32 v64, v106, v64
	v_add_f32_e32 v66, 1.0, v66
	v_log_f32_e32 v66, v66
	s_nop 0
	v_fmac_f32_e32 v65, 0x3f317218, v66
	v_cndmask_b32_e64 v108, 0, -v65, vcc
	v_fma_f32 v65, v67, s70, -v65
	v_add_f32_e32 v64, v108, v64
	v_cndmask_b32_e32 v109, v241, v65, vcc
	ds_bpermute_b32 v65, v88, v64
	ds_bpermute_b32 v67, v89, v64
	ds_bpermute_b32 v85, v90, v64
	s_waitcnt lgkmcnt(2)
	v_add_f32_e32 v64, v64, v65
	v_cndmask_b32_e64 v66, 0, v65, s[6:7]
	v_add_u32_e32 v65, 32, v91
	v_cmp_lt_i32_e32 vcc, v65, v72
	v_mul_f32_e32 v65, 0x3e000000, v60
	s_waitcnt lgkmcnt(1)
	v_add_f32_e32 v71, v64, v67
	v_cndmask_b32_e64 v86, 0, v67, s[8:9]
	v_mul_f32_e64 v67, |v65|, s80
	v_exp_f32_e32 v67, v67
	v_max_f32_e32 v65, 0, v65
	s_waitcnt lgkmcnt(0)
	v_cndmask_b32_e64 v64, 0, v85, s[10:11]
	v_add_f32_e32 v67, 1.0, v67
	v_log_f32_e32 v67, v67
	s_nop 0
	v_fmac_f32_e32 v65, 0x3f317218, v67
	v_fma_f32 v60, v60, s70, -v65
	v_cndmask_b32_e32 v110, v241, v60, vcc
	v_sub_f32_e32 v60, 0, v65
	v_add_u32_e32 v65, 33, v91
	v_cndmask_b32_e32 v60, 0, v60, vcc
	v_cmp_lt_i32_e32 vcc, v65, v72
	v_mul_f32_e32 v65, 0x3e000000, v61
	v_mul_f32_e64 v67, |v65|, s80
	v_exp_f32_e32 v67, v67
	v_max_f32_e32 v65, 0, v65
	v_add_f32_e32 v67, 1.0, v67
	v_log_f32_e32 v67, v67
	s_nop 0
	v_fmac_f32_e32 v65, 0x3f317218, v67
	v_fma_f32 v61, v61, s70, -v65
	v_cndmask_b32_e32 v112, v241, v61, vcc
	v_add_u32_e32 v61, 34, v91
	v_cndmask_b32_e64 v111, 0, -v65, vcc
	v_cmp_lt_i32_e32 vcc, v61, v72
	v_mul_f32_e32 v61, 0x3e000000, v62
	v_mul_f32_e64 v65, |v61|, s80
	v_exp_f32_e32 v65, v65
	v_max_f32_e32 v61, 0, v61
	v_add_f32_e32 v60, v111, v60
	v_add_f32_e32 v65, 1.0, v65
	v_log_f32_e32 v65, v65
	s_nop 0
	v_fmac_f32_e32 v61, 0x3f317218, v65
	v_cndmask_b32_e64 v113, 0, -v61, vcc
	v_fma_f32 v61, v62, s70, -v61
	v_cndmask_b32_e32 v114, v241, v61, vcc
	v_add_u32_e32 v61, 35, v91
	v_cmp_lt_i32_e32 vcc, v61, v72
	v_mul_f32_e32 v61, 0x3e000000, v63
	v_mul_f32_e64 v62, |v61|, s80
	v_exp_f32_e32 v62, v62
	v_max_f32_e32 v61, 0, v61
	v_add_f32_e32 v60, v113, v60
	v_add_f32_e32 v62, 1.0, v62
	v_log_f32_e32 v62, v62
	s_nop 0
	v_fmac_f32_e32 v61, 0x3f317218, v62
	v_cndmask_b32_e64 v117, 0, -v61, vcc
	v_fma_f32 v61, v63, s70, -v61
	v_add_f32_e32 v60, v117, v60
	v_cndmask_b32_e32 v118, v241, v61, vcc
	ds_bpermute_b32 v61, v88, v60
	ds_bpermute_b32 v62, v89, v60
	ds_bpermute_b32 v87, v90, v60
	s_waitcnt lgkmcnt(2)
	v_add_f32_e32 v60, v60, v61
	s_waitcnt lgkmcnt(1)
	v_add_f32_e32 v67, v60, v62
	v_cndmask_b32_e64 v60, 0, v61, s[6:7]
	v_add_u32_e32 v61, 48, v91
	v_cmp_lt_i32_e32 vcc, v61, v72
	v_mul_f32_e32 v61, 0x3e000000, v56
	v_mul_f32_e64 v63, |v61|, s80
	v_exp_f32_e32 v63, v63
	v_max_f32_e32 v61, 0, v61
	v_cndmask_b32_e64 v62, 0, v62, s[8:9]
	s_waitcnt lgkmcnt(0)
	v_cndmask_b32_e64 v82, 0, v87, s[10:11]
	v_add_f32_e32 v63, 1.0, v63
	v_log_f32_e32 v63, v63
	s_nop 0
	v_fmac_f32_e32 v61, 0x3f317218, v63
	v_fma_f32 v56, v56, s70, -v61
	v_cndmask_b32_e32 v119, v241, v56, vcc
	v_sub_f32_e32 v56, 0, v61
	v_add_u32_e32 v61, 49, v91
	v_cndmask_b32_e32 v56, 0, v56, vcc
	v_cmp_lt_i32_e32 vcc, v61, v72
	v_mul_f32_e32 v61, 0x3e000000, v57
	v_mul_f32_e64 v63, |v61|, s80
	v_exp_f32_e32 v63, v63
	v_max_f32_e32 v61, 0, v61
	v_add_f32_e32 v63, 1.0, v63
	v_log_f32_e32 v63, v63
	s_nop 0
	v_fmac_f32_e32 v61, 0x3f317218, v63
	v_fma_f32 v57, v57, s70, -v61
	v_cndmask_b32_e32 v121, v241, v57, vcc
	v_add_u32_e32 v57, 50, v91
	v_cndmask_b32_e64 v120, 0, -v61, vcc
	v_cmp_lt_i32_e32 vcc, v57, v72
	v_mul_f32_e32 v57, 0x3e000000, v58
	v_mul_f32_e64 v61, |v57|, s80
	v_exp_f32_e32 v61, v61
	v_max_f32_e32 v57, 0, v57
	v_add_f32_e32 v56, v120, v56
	v_add_f32_e32 v61, 1.0, v61
	v_log_f32_e32 v61, v61
	s_nop 0
	v_fmac_f32_e32 v57, 0x3f317218, v61
	v_cndmask_b32_e64 v122, 0, -v57, vcc
	v_fma_f32 v57, v58, s70, -v57
	v_cndmask_b32_e32 v123, v241, v57, vcc
	v_add_u32_e32 v57, 51, v91
	v_cmp_lt_i32_e32 vcc, v57, v72
	v_mul_f32_e32 v57, 0x3e000000, v59
	v_mul_f32_e64 v58, |v57|, s80
	v_exp_f32_e32 v58, v58
	v_max_f32_e32 v57, 0, v57
	v_add_f32_e32 v56, v122, v56
	v_add_f32_e32 v58, 1.0, v58
	v_log_f32_e32 v58, v58
	s_nop 0
	v_fmac_f32_e32 v57, 0x3f317218, v58
	v_cndmask_b32_e64 v124, 0, -v57, vcc
	v_fma_f32 v57, v59, s70, -v57
	v_add_f32_e32 v56, v124, v56
	v_cndmask_b32_e32 v125, v241, v57, vcc
	ds_bpermute_b32 v57, v88, v56
	ds_bpermute_b32 v58, v89, v56
	ds_bpermute_b32 v63, v90, v56
	s_waitcnt lgkmcnt(2)
	v_add_f32_e32 v56, v56, v57
	s_waitcnt lgkmcnt(1)
	v_add_f32_e32 v61, v56, v58
	v_cndmask_b32_e64 v56, 0, v57, s[6:7]
	v_cndmask_b32_e64 v57, 0, v58, s[8:9]
	v_add_f32_e32 v56, v56, v57
	s_waitcnt lgkmcnt(0)
	v_cndmask_b32_e64 v57, 0, v63, s[10:11]
	v_add_f32_e32 v56, v56, v57
	v_add_f32_e32 v126, v83, v56
	v_pk_add_f32 v[56:57], v[60:61], v[62:63]
	v_pk_add_f32 v[58:59], v[66:67], v[86:87]
	v_pk_add_f32 v[60:61], v[56:57], v[82:83]
	v_add_f32_e32 v82, v124, v126
	v_mov_b32_e32 v65, v61
	v_pk_add_f32 v[62:63], v[58:59], v[64:65]
	v_add_f32_e32 v56, v60, v61
	v_pk_add_f32 v[60:61], v[70:71], v[84:85]
	v_mov_b32_e32 v69, v63
	v_add_f32_e32 v58, v62, v63
	v_pk_add_f32 v[62:63], v[60:61], v[68:69]
	v_add_f32_e32 v65, v109, v58
	v_add_f32_e32 v60, v62, v63
	v_add_f32_e32 v62, v102, v60
	v_mul_f32_e32 v62, 0x3fb8aa3b, v62
	v_add_f32_e32 v60, v101, v60
	v_exp_f32_e32 v63, v62
	v_add_f32_e32 v62, v100, v60
	v_add_f32_e32 v58, v108, v58
	v_mul_f32_e32 v62, 0x3fb8aa3b, v62
	v_add_f32_e32 v60, v99, v60
	v_add_f32_e32 v66, v107, v58
	v_add_f32_e32 v58, v106, v58
	v_exp_f32_e32 v64, v62
	v_add_f32_e32 v62, v98, v60
	v_add_f32_e32 v60, v97, v60
	v_add_f32_e32 v67, v105, v58
	v_add_f32_e32 v58, v104, v58
	v_add_f32_e32 v60, v92, v60
	v_add_f32_e32 v58, v103, v58
	v_mul_f32_e32 v62, 0x3fb8aa3b, v62
	v_mul_f32_e32 v60, 0x3fb8aa3b, v60
	v_mul_f32_e32 v65, 0x3fb8aa3b, v65
	v_mul_f32_e32 v66, 0x3fb8aa3b, v66
	v_mul_f32_e32 v67, 0x3fb8aa3b, v67
	v_mul_f32_e32 v58, 0x3fb8aa3b, v58
	v_add_f32_e32 v68, v118, v56
	v_add_f32_e32 v56, v117, v56
	v_exp_f32_e32 v62, v62
	v_exp_f32_e32 v60, v60
	v_exp_f32_e32 v65, v65
	v_exp_f32_e32 v66, v66
	v_exp_f32_e32 v67, v67
	v_exp_f32_e32 v58, v58
	v_add_f32_e32 v69, v114, v56
	v_add_f32_e32 v56, v113, v56
	v_add_f32_e32 v84, v123, v82
	v_add_f32_e32 v82, v122, v82
	v_add_f32_e32 v70, v112, v56
	v_add_f32_e32 v56, v111, v56
	v_add_f32_e32 v85, v121, v82
	v_add_f32_e32 v82, v120, v82
	v_add_f32_e32 v56, v110, v56
	v_add_f32_e32 v71, v125, v126
	v_add_f32_e32 v82, v119, v82
	v_mul_f32_e32 v68, 0x3fb8aa3b, v68
	v_mul_f32_e32 v69, 0x3fb8aa3b, v69
	v_mul_f32_e32 v70, 0x3fb8aa3b, v70
	v_mul_f32_e32 v56, 0x3fb8aa3b, v56
	v_mul_f32_e32 v71, 0x3fb8aa3b, v71
	v_mul_f32_e32 v84, 0x3fb8aa3b, v84
	v_mul_f32_e32 v85, 0x3fb8aa3b, v85
	v_mul_f32_e32 v82, 0x3fb8aa3b, v82
	v_exp_f32_e32 v68, v68
	v_exp_f32_e32 v69, v69
	v_exp_f32_e32 v70, v70
	v_exp_f32_e32 v56, v56
	v_exp_f32_e32 v71, v71
	v_exp_f32_e32 v84, v84
	v_exp_f32_e32 v85, v85
	v_exp_f32_e32 v82, v82
	v_cvt_pk_bf16_f32 v62, v60, v62
	v_cvt_pk_bf16_f32 v63, v64, v63
	v_cvt_pk_bf16_f32 v64, v58, v67
	v_cvt_pk_bf16_f32 v65, v66, v65
	v_cvt_pk_bf16_f32 v66, v56, v70
	v_cvt_pk_bf16_f32 v67, v69, v68
	v_mfma_f32_16x16x32_bf16 v[0:3], v[52:55], v[62:65], v[0:3]
	v_cvt_pk_bf16_f32 v68, v82, v85
	v_cvt_pk_bf16_f32 v69, v84, v71
	v_mfma_f32_16x16x32_bf16 v[4:7], v[44:47], v[62:65], v[4:7]
	v_mfma_f32_16x16x32_bf16 v[8:11], v[36:39], v[62:65], v[8:11]
	v_mfma_f32_16x16x32_bf16 v[12:15], v[28:31], v[62:65], v[12:15]
	v_mfma_f32_16x16x32_bf16 v[0:3], v[48:51], v[66:69], v[0:3]
	v_mfma_f32_16x16x32_bf16 v[4:7], v[40:43], v[66:69], v[4:7]
	v_mfma_f32_16x16x32_bf16 v[8:11], v[32:35], v[66:69], v[8:11]
	v_mfma_f32_16x16x32_bf16 v[12:15], v[24:27], v[66:69], v[12:15]
	s_cbranch_scc0 .Lcc_last
	v_add_f32_e32 v24, v93, v94
	v_add_f32_e32 v24, v24, v95
	v_add_f32_e32 v24, v24, v96
	v_add_f32_e32 v24, v24, v61
	v_add_f32_e32 v24, v24, v59
	v_add_f32_e32 v24, v24, v57
	v_add_f32_e32 v83, v83, v24
	v_cmp_lt_f32_e32 vcc, s38, v83
	s_cbranch_vccnz .Lcc_after
.Lcc_last:
	s_mov_b32 s15, 1
.Lcc_after:
	s_cmp_eq_u32 s13, 0
	s_cbranch_scc1 .Lcc_nostore
	s_xor_b32 s20, s14, 0x5000
	v_add_u32_e32 v135, s20, v128
	s_waitcnt vmcnt(0)
	ds_write_b128 v135, v[140:143] offset:16384
	ds_write_b128 v135, v[144:147] offset:26624
.Lcc_nostore:
	s_xor_b32 s20, s15, 1
	v_mov_b32_e32 v135, s20
	v_add_u32_e32 v134, s21, v156
	ds_write_b32 v134, v135 offset:8448
	s_waitcnt lgkmcnt(0)
	s_barrier
	s_cmp_eq_u32 s13, 0
	s_cbranch_scc1 .LBB0_402
	v_mov_b32_e32 v134, s21
	ds_read_b128 v[148:151], v134 offset:8448
	ds_read_b128 v[152:155], v134 offset:8464
	s_waitcnt lgkmcnt(0)
	v_or3_b32 v148, v148, v149, v150
	v_or3_b32 v148, v148, v151, v152
	v_or3_b32 v148, v148, v153, v154
	v_or_b32_e32 v148, v148, v155
	s_nop 0
	v_readfirstlane_b32 s20, v148
	s_cmp_eq_u32 s20, 0
	s_cbranch_scc1 .LBB0_402
	s_add_i32 s13, s13, -1
	s_xor_b32 s14, s14, 0x5000
	s_xor_b32 s21, s21, 32
	s_branch .Lcc_step
